# strategy 5: direct HBM->LDS (LDS-DMA) staging of the postscan token-shift and group-norm weight rows
# speedup vs baseline: 1.0072x; 1.0072x over previous
.LBB0_93:
	s_andn2_b64 vcc, exec, s[4:5]
	s_cbranch_vccnz .LBB0_151
	v_readlane_b32 s4, v254, 41
	v_readlane_b32 s5, v254, 42
	s_load_dwordx2 s[0:1], s[4:5], 0x48
	s_nop 0
	s_load_dwordx2 s[4:5], s[4:5], 0x120
	v_readlane_b32 s6, v254, 53
	v_readlane_b32 s7, v254, 54
	s_mov_b32 s8, s6
	s_mul_i32 s7, s8, 0xa200
	s_mul_hi_i32 s6, s6, 0xa200
	v_mov_b32_e32 v16, v197
	s_waitcnt lgkmcnt(0)
	s_add_u32 s16, s0, s7
	s_movk_i32 s0, 0x2400
	s_addc_u32 s17, s1, s6
	s_nop 0
	v_cmp_gt_i32_e32 vcc, s0, v16
	s_barrier
	v_readlane_b32 s0, v254, 41
	v_readlane_b32 s1, v254, 42
	v_readlane_b32 s6, v254, 53
	v_readfirstlane_b32 s7, v197
	s_load_dwordx4 s[36:39], s[0:1], 0x88
	s_load_dwordx2 s[40:41], s[0:1], 0x98
	v_and_b32_e32 v3, 63, v197
	v_lshlrev_b32_e32 v3, 4, v3
	s_lshl_b32 s6, s6, 12
	s_lshr_b32 s7, s7, 6
	s_mul_i32 s8, s7, 6
	s_waitcnt lgkmcnt(0)
	s_add_u32 s36, s36, s6
	s_addc_u32 s37, s37, 0
	s_add_u32 s38, s38, s6
	s_addc_u32 s39, s39, 0
	s_add_u32 s40, s40, s6
	s_addc_u32 s41, s41, 0
	s_mov_b32 s23, s8
	s_lshr_b32 s24, s23, 2
	s_and_b32 s25, s23, 3
	s_cmp_lt_u32 s24, 9
	s_cbranch_scc0 .Lpsd_g0
	s_mul_hi_u32 s26, s24, 0x55555556
	s_mul_i32 s27, s26, 3
	s_sub_u32 s27, s24, s27
	s_mul_i32 s27, s27, 0x3600
	s_lshl_b32 s26, s26, 12
	s_add_u32 s27, s27, s26
	s_add_u32 s28, s16, s27
	s_addc_u32 s29, s17, 0
	s_branch .Lpsd_s0
.Lpsd_g0:
	s_cmp_eq_u32 s24, 9
	s_cselect_b32 s28, s38, s36
	s_cselect_b32 s29, s39, s37
	s_cmp_eq_u32 s24, 10
	s_cselect_b32 s28, s40, s28
	s_cselect_b32 s29, s41, s29
.Lpsd_s0:
	s_lshl_b32 s25, s25, 10
	s_add_u32 s28, s28, s25
	s_addc_u32 s29, s29, 0
	s_lshl_b32 s30, s24, 12
	s_add_u32 s30, s30, s25
	s_mov_b32 m0, s30
	s_nop 0
	global_load_lds_dwordx4 v3, s[28:29]
	s_add_i32 s23, s8, 1
	s_lshr_b32 s24, s23, 2
	s_and_b32 s25, s23, 3
	s_cmp_lt_u32 s24, 9
	s_cbranch_scc0 .Lpsd_g1
	s_mul_hi_u32 s26, s24, 0x55555556
	s_mul_i32 s27, s26, 3
	s_sub_u32 s27, s24, s27
	s_mul_i32 s27, s27, 0x3600
	s_lshl_b32 s26, s26, 12
	s_add_u32 s27, s27, s26
	s_add_u32 s28, s16, s27
	s_addc_u32 s29, s17, 0
	s_branch .Lpsd_s1

.Lpsd_s1:
	s_lshl_b32 s25, s25, 10
	s_add_u32 s28, s28, s25
	s_addc_u32 s29, s29, 0
	s_lshl_b32 s30, s24, 12
	s_add_u32 s30, s30, s25
	s_mov_b32 m0, s30
	s_nop 0
	global_load_lds_dwordx4 v3, s[28:29]
	s_add_i32 s23, s8, 2
	s_lshr_b32 s24, s23, 2
	s_and_b32 s25, s23, 3
	s_cmp_lt_u32 s24, 9
	s_cbranch_scc0 .Lpsd_g2
	s_mul_hi_u32 s26, s24, 0x55555556
	s_mul_i32 s27, s26, 3
	s_sub_u32 s27, s24, s27
	s_mul_i32 s27, s27, 0x3600
	s_lshl_b32 s26, s26, 12
	s_add_u32 s27, s27, s26
	s_add_u32 s28, s16, s27
	s_addc_u32 s29, s17, 0
	s_branch .Lpsd_s2

.Lpsd_s2:
	s_lshl_b32 s25, s25, 10
	s_add_u32 s28, s28, s25
	s_addc_u32 s29, s29, 0
	s_lshl_b32 s30, s24, 12
	s_add_u32 s30, s30, s25
	s_mov_b32 m0, s30
	s_nop 0
	global_load_lds_dwordx4 v3, s[28:29]
	s_add_i32 s23, s8, 3
	s_lshr_b32 s24, s23, 2
	s_and_b32 s25, s23, 3
	s_cmp_lt_u32 s24, 9
	s_cbranch_scc0 .Lpsd_g3
	s_mul_hi_u32 s26, s24, 0x55555556
	s_mul_i32 s27, s26, 3
	s_sub_u32 s27, s24, s27
	s_mul_i32 s27, s27, 0x3600
	s_lshl_b32 s26, s26, 12
	s_add_u32 s27, s27, s26
	s_add_u32 s28, s16, s27
	s_addc_u32 s29, s17, 0
	s_branch .Lpsd_s3

.Lpsd_s3:
	s_lshl_b32 s25, s25, 10
	s_add_u32 s28, s28, s25
	s_addc_u32 s29, s29, 0
	s_lshl_b32 s30, s24, 12
	s_add_u32 s30, s30, s25
	s_mov_b32 m0, s30
	s_nop 0
	global_load_lds_dwordx4 v3, s[28:29]
	s_add_i32 s23, s8, 4
	s_lshr_b32 s24, s23, 2
	s_and_b32 s25, s23, 3
	s_cmp_lt_u32 s24, 9
	s_cbranch_scc0 .Lpsd_g4
	s_mul_hi_u32 s26, s24, 0x55555556
	s_mul_i32 s27, s26, 3
	s_sub_u32 s27, s24, s27
	s_mul_i32 s27, s27, 0x3600
	s_lshl_b32 s26, s26, 12
	s_add_u32 s27, s27, s26
	s_add_u32 s28, s16, s27
	s_addc_u32 s29, s17, 0
	s_branch .Lpsd_s4

.Lpsd_s4:
	s_lshl_b32 s25, s25, 10
	s_add_u32 s28, s28, s25
	s_addc_u32 s29, s29, 0
	s_lshl_b32 s30, s24, 12
	s_add_u32 s30, s30, s25
	s_mov_b32 m0, s30
	s_nop 0
	global_load_lds_dwordx4 v3, s[28:29]
	s_add_i32 s23, s8, 5
	s_lshr_b32 s24, s23, 2
	s_and_b32 s25, s23, 3
	s_cmp_lt_u32 s24, 9
	s_cbranch_scc0 .Lpsd_g5
	s_mul_hi_u32 s26, s24, 0x55555556
	s_mul_i32 s27, s26, 3
	s_sub_u32 s27, s24, s27
	s_mul_i32 s27, s27, 0x3600
	s_lshl_b32 s26, s26, 12
	s_add_u32 s27, s27, s26
	s_add_u32 s28, s16, s27
	s_addc_u32 s29, s17, 0
	s_branch .Lpsd_s5

.Lpsd_s5:
	s_lshl_b32 s25, s25, 10
	s_add_u32 s28, s28, s25
	s_addc_u32 s29, s29, 0
	s_lshl_b32 s30, s24, 12
	s_add_u32 s30, s30, s25
	s_mov_b32 m0, s30
	s_nop 0
	global_load_lds_dwordx4 v3, s[28:29]
	s_waitcnt vmcnt(0)
	v_readlane_b32 s0, v253, 8
	v_readlane_b32 s1, v253, 9
	s_and_b64 vcc, exec, s[0:1]
	s_cbranch_vccz .LBB0_151
	v_lshlrev_b32_e32 v17, 3, v16
	s_waitcnt vmcnt(0)
	v_and_b32_e32 v18, 0x78, v17
	v_lshlrev_b32_e32 v4, 2, v18
	v_mov_b32_e32 v5, v2
	v_lshl_add_u64 v[12:13], s[16:17], 0, v[4:5]
	v_add_co_u32_e32 v4, vcc, 0x3000, v12
	s_mov_b64 s[0:1], 0x3400
	s_nop 0
	v_addc_co_u32_e32 v5, vcc, 0, v13, vcc
	v_lshl_add_u64 v[8:9], v[12:13], 0, s[0:1]
	v_add_co_u32_e32 v14, vcc, 0x6000, v12
	v_readlane_b32 s0, v254, 53
	s_nop 0
	v_addc_co_u32_e32 v15, vcc, 0, v13, vcc
	v_readlane_b32 s1, v254, 54
	v_add_co_u32_e32 v20, vcc, 0xa000, v12
	s_cmp_eq_u32 s0, 3
	s_mov_b64 s[0:1], 0xa004
	v_addc_co_u32_e32 v21, vcc, 0, v13, vcc
	v_lshl_add_u64 v[24:25], v[12:13], 0, s[0:1]
	s_mov_b64 s[0:1], 0x6a04
	global_load_dwordx4 v[4:7], v[4:5], off offset:1024
	s_nop 0
	global_load_dwordx4 v[8:11], v[8:9], off offset:16
	v_lshl_add_u64 v[28:29], v[12:13], 0, s[0:1]
	global_load_dword v1, v[14:15], off offset:2560
	global_load_dword v3, v[20:21], off
	s_nop 0
	global_load_dwordx4 v[20:23], v[20:21], off offset:4
	s_nop 0
	global_load_dwordx3 v[24:26], v[24:25], off offset:16
	s_nop 0
	global_load_dwordx4 v[12:15], v[14:15], off offset:2564
	s_nop 0
	global_load_dwordx3 v[156:158], v[28:29], off offset:16
	v_lshlrev_b32_e32 v29, 1, v16
	v_and_b32_e32 v19, 15, v16
	v_bfe_u32 v27, v16, 4, 2
	v_and_b32_e32 v31, 0xffffff80, v29
	v_ashrrev_i32_e32 v199, 4, v16
	s_movk_i32 s0, 0x110
	v_lshlrev_b32_e32 v28, 4, v27
	v_or_b32_e32 v30, v31, v19
	v_mov_b32_e32 v29, v2
	v_mul_lo_u32 v37, v199, s0
	v_add_u32_e32 v38, 0, v28
	v_lshl_add_u64 v[28:29], s[4:5], 0, v[28:29]
	s_mov_b64 s[0:1], 0x3958100
	v_lshlrev_b32_e32 v39, 1, v31
	v_ashrrev_i32_e32 v31, 31, v30
	v_lshl_add_u64 v[28:29], v[28:29], 0, s[0:1]
	v_lshlrev_b64 v[32:33], 8, v[30:31]
	v_lshl_add_u64 v[160:161], v[28:29], 0, v[32:33]
	v_or_b32_e32 v32, 16, v30
	v_ashrrev_i32_e32 v33, 31, v32
	v_lshlrev_b64 v[32:33], 8, v[32:33]
	v_lshl_add_u64 v[162:163], v[28:29], 0, v[32:33]
	v_or_b32_e32 v32, 32, v30
	v_ashrrev_i32_e32 v33, 31, v32
	v_lshlrev_b64 v[32:33], 8, v[32:33]
	v_lshl_add_u64 v[164:165], v[28:29], 0, v[32:33]
	v_or_b32_e32 v32, 48, v30
	v_ashrrev_i32_e32 v33, 31, v32
	v_lshlrev_b64 v[32:33], 8, v[32:33]
	v_lshl_add_u64 v[166:167], v[28:29], 0, v[32:33]
	v_or_b32_e32 v32, 64, v30
	v_ashrrev_i32_e32 v33, 31, v32
	v_lshlrev_b64 v[32:33], 8, v[32:33]
	v_lshl_add_u64 v[168:169], v[28:29], 0, v[32:33]
	v_or_b32_e32 v32, 0x50, v30
	v_ashrrev_i32_e32 v33, 31, v32
	v_lshlrev_b32_e32 v34, 1, v19
	v_ashrrev_i32_e32 v40, 7, v16
	v_lshlrev_b64 v[32:33], 8, v[32:33]
	v_lshlrev_b32_e32 v16, 4, v16
	s_waitcnt lgkmcnt(0)
	s_cselect_b64 s[12:13], -1, 0
	s_add_u32 s14, s4, 0x11198100
	v_add_u32_e32 v35, 0, v34
	v_and_b32_e32 v17, 0x3f8, v17
	v_lshlrev_b32_e32 v31, 13, v27
	s_movk_i32 s0, 0x1ff0
	v_lshl_add_u64 v[170:171], v[28:29], 0, v[32:33]
	v_or_b32_e32 v32, 0x60, v30
	v_or_b32_e32 v30, 0x70, v30
	v_and_b32_e32 v182, 0x7f0, v16
	s_addc_u32 s15, s5, 0
	v_lshlrev_b32_e32 v41, 1, v17
	v_add3_u32 v200, v35, v39, v31
	v_mad_u32_u24 v27, v27, s0, v38
	v_ashrrev_i32_e32 v33, 31, v32
	v_ashrrev_i32_e32 v31, 31, v30
	v_lshl_or_b32 v16, v40, 11, v182
	s_add_i32 s0, 0, 0xe200
	v_lshl_add_u32 v36, v18, 1, 0
	v_add_u32_e32 v42, 0, v41
	v_mul_u32_u24_e32 v19, 0x110, v19
	v_add3_u32 v27, v27, v39, v34
	v_lshlrev_b64 v[32:33], 8, v[32:33]
	v_lshlrev_b64 v[30:31], 8, v[30:31]
	v_add_u32_e32 v206, s0, v16
	v_readlane_b32 s0, v253, 24
	v_add_u32_e32 v201, 0xe200, v27
	v_add_u32_e32 v202, 0xea00, v27
	v_add_u32_e32 v203, 0xf200, v27
	v_add_u32_e32 v204, 0xfa00, v27
	v_lshl_add_u64 v[172:173], v[28:29], 0, v[32:33]
	v_lshl_add_u64 v[174:175], v[28:29], 0, v[30:31]
	v_lshl_add_u32 v205, v17, 2, 0
	v_mov_b32_e32 v183, v2
	v_add_u32_e32 v184, s0, v40
	v_lshlrev_b32_e32 v186, 1, v18
	v_add_u32_e32 v207, v36, v37
	s_waitcnt vmcnt(3)
	v_mov_b32_e32 v179, v23
	s_waitcnt vmcnt(2)
	v_mov_b32_e32 v159, v26
	s_waitcnt vmcnt(0)
	v_mov_b32_e32 v176, v157
	v_mov_b32_e32 v177, v25
	v_mov_b32_e32 v157, v24
	v_mov_b32_e32 v178, v15
	v_mov_b32_e32 v15, v22
	v_mov_b32_e32 v180, v13
	v_mov_b32_e32 v181, v21
	v_mov_b32_e32 v13, v20
	v_add_u32_e32 v208, v38, v19
	v_add_u32_e32 v209, v42, v41
	s_mov_b32 s0, s2
	s_branch .LBB0_124
